# weight-transpose helper issues its loads before waiting for the qkv tile's stores to drain
# speedup vs baseline: 1.0109x; 1.0022x over previous
.Lwh_entry:
	s_cmp_lg_u32 s54, 8
	s_cbranch_scc1 .LBB0_664
	s_cmpk_gt_i32 s0, 0xaf
	s_cbranch_scc1 .LBB0_664
	s_mov_b64 exec, -1
	s_waitcnt lgkmcnt(0)
	s_barrier
	s_lshr_b32 s4, s0, 4
	s_and_b32 s5, s0, 15
	s_load_dwordx2 s[24:25], s[72:73], 0xd8
	s_lshl_b32 s28, s4, 20
	s_lshl_b32 s29, s5, 8
	s_add_u32 s28, s28, s29
	s_add_u32 s28, s28, 0x1600000
	s_waitcnt lgkmcnt(0)
	s_add_u32 s24, s24, s28
	s_addc_u32 s25, s25, 0
	v_lshrrev_b32_e32 v40, 4, v156
	v_and_b32_e32 v41, 15, v156
	v_lshlrev_b32_e32 v41, 4, v41
	v_lshl_add_u32 v42, v40, 12, v41
	global_load_dwordx4 v[0:3], v42, s[24:25] nt
	s_add_u32 s24, s24, 0x20000
	s_addc_u32 s25, s25, 0
	global_load_dwordx4 v[4:7], v42, s[24:25] nt
	s_add_u32 s24, s24, 0x20000
	s_addc_u32 s25, s25, 0
	global_load_dwordx4 v[8:11], v42, s[24:25] nt
	s_add_u32 s24, s24, 0x20000
	s_addc_u32 s25, s25, 0
	global_load_dwordx4 v[12:15], v42, s[24:25] nt
	s_add_u32 s24, s24, 0x20000
	s_addc_u32 s25, s25, 0
	global_load_dwordx4 v[16:19], v42, s[24:25] nt
	s_add_u32 s24, s24, 0x20000
	s_addc_u32 s25, s25, 0
	global_load_dwordx4 v[20:23], v42, s[24:25] nt
	s_add_u32 s24, s24, 0x20000
	s_addc_u32 s25, s25, 0
	global_load_dwordx4 v[24:27], v42, s[24:25] nt
	s_add_u32 s24, s24, 0x20000
	s_addc_u32 s25, s25, 0
	global_load_dwordx4 v[28:31], v42, s[24:25] nt
	v_mul_u32_u24_e32 v43, 0x104, v40
	v_add_u32_e32 v43, v43, v41
	s_waitcnt vmcnt(7)
	ds_write2_b32 v43, v0, v1 offset1:1
	ds_write2_b32 v43, v2, v3 offset0:2 offset1:3
	v_add_u32_e32 v43, 0x2080, v43
	s_waitcnt vmcnt(6)
	ds_write2_b32 v43, v4, v5 offset1:1
	ds_write2_b32 v43, v6, v7 offset0:2 offset1:3
	v_add_u32_e32 v43, 0x2080, v43
	s_waitcnt vmcnt(5)
	ds_write2_b32 v43, v8, v9 offset1:1
	ds_write2_b32 v43, v10, v11 offset0:2 offset1:3
	v_add_u32_e32 v43, 0x2080, v43
	s_waitcnt vmcnt(4)
	ds_write2_b32 v43, v12, v13 offset1:1
	ds_write2_b32 v43, v14, v15 offset0:2 offset1:3
	v_add_u32_e32 v43, 0x2080, v43
	s_waitcnt vmcnt(3)
	ds_write2_b32 v43, v16, v17 offset1:1
	ds_write2_b32 v43, v18, v19 offset0:2 offset1:3
	v_add_u32_e32 v43, 0x2080, v43
	s_waitcnt vmcnt(2)
	ds_write2_b32 v43, v20, v21 offset1:1
	ds_write2_b32 v43, v22, v23 offset0:2 offset1:3
	v_add_u32_e32 v43, 0x2080, v43
	s_waitcnt vmcnt(1)
	ds_write2_b32 v43, v24, v25 offset1:1
	ds_write2_b32 v43, v26, v27 offset0:2 offset1:3
	v_add_u32_e32 v43, 0x2080, v43
	s_waitcnt vmcnt(0)
	ds_write2_b32 v43, v28, v29 offset1:1
	ds_write2_b32 v43, v30, v31 offset0:2 offset1:3
	s_waitcnt lgkmcnt(0)
	s_barrier
	v_lshrrev_b32_e32 v40, 3, v156
	v_and_b32_e32 v41, 7, v156
	v_mul_u32_u24_e32 v45, 0x820, v41
	v_lshl_add_u32 v45, v40, 2, v45
	v_and_b32_e32 v46, 32, v40
	v_bfe_u32 v47, v40, 2, 1
	v_lshl_add_u32 v46, v47, 4, v46
	v_bfe_u32 v47, v40, 3, 2
	v_lshl_add_u32 v46, v47, 2, v46
	v_and_b32_e32 v47, 3, v40
	v_add_u32_e32 v46, v46, v47
	v_mul_u32_u24_e32 v46, 0x1600, v46
	v_lshl_add_u32 v46, v41, 4, v46
	s_mul_i32 s28, s5, 0x58000
	s_lshl_b32 s29, s4, 9
	s_add_u32 s28, s28, s29
	s_add_u32 s28, s28, 0x5104000
	s_add_u32 s24, s48, s28
	s_addc_u32 s25, s49, 0
	v_add_u32_e32 v48, 0x0, v45
	ds_read2_b32 v[32:33], v48 offset1:65
	ds_read2_b32 v[34:35], v48 offset0:130 offset1:195
	v_add_u32_e32 v49, 0x410, v48
	ds_read2_b32 v[36:37], v49 offset1:65
	ds_read2_b32 v[38:39], v49 offset0:130 offset1:195
	s_waitcnt lgkmcnt(0)
	v_cvt_pk_bf16_f32 v32, v32, v33
	v_cvt_pk_bf16_f32 v33, v34, v35
	v_cvt_pk_bf16_f32 v34, v36, v37
	v_cvt_pk_bf16_f32 v35, v38, v39
	global_store_dwordx4 v46, v[32:35], s[24:25]
	s_nop 1
	v_add_u32_e32 v48, 0x4100, v45
	ds_read2_b32 v[32:33], v48 offset1:65
	ds_read2_b32 v[34:35], v48 offset0:130 offset1:195
	v_add_u32_e32 v49, 0x410, v48
	ds_read2_b32 v[36:37], v49 offset1:65
	ds_read2_b32 v[38:39], v49 offset0:130 offset1:195
	s_waitcnt lgkmcnt(0)
	v_cvt_pk_bf16_f32 v32, v32, v33
	v_cvt_pk_bf16_f32 v33, v34, v35
	v_cvt_pk_bf16_f32 v34, v36, v37
	v_cvt_pk_bf16_f32 v35, v38, v39
	global_store_dwordx4 v46, v[32:35], s[24:25] offset:128
	s_nop 1
	v_add_u32_e32 v48, 0x8200, v45
	ds_read2_b32 v[32:33], v48 offset1:65
	ds_read2_b32 v[34:35], v48 offset0:130 offset1:195
	v_add_u32_e32 v49, 0x410, v48
	ds_read2_b32 v[36:37], v49 offset1:65
	ds_read2_b32 v[38:39], v49 offset0:130 offset1:195
	s_waitcnt lgkmcnt(0)
	v_cvt_pk_bf16_f32 v32, v32, v33
	v_cvt_pk_bf16_f32 v33, v34, v35
	v_cvt_pk_bf16_f32 v34, v36, v37
	v_cvt_pk_bf16_f32 v35, v38, v39
	global_store_dwordx4 v46, v[32:35], s[24:25] offset:256
	s_nop 1
	v_add_u32_e32 v48, 0xc300, v45
	ds_read2_b32 v[32:33], v48 offset1:65
	ds_read2_b32 v[34:35], v48 offset0:130 offset1:195
	v_add_u32_e32 v49, 0x410, v48
	ds_read2_b32 v[36:37], v49 offset1:65
	ds_read2_b32 v[38:39], v49 offset0:130 offset1:195
	s_waitcnt lgkmcnt(0)
	v_cvt_pk_bf16_f32 v32, v32, v33
	v_cvt_pk_bf16_f32 v33, v34, v35
	v_cvt_pk_bf16_f32 v34, v36, v37
	v_cvt_pk_bf16_f32 v35, v38, v39
	global_store_dwordx4 v46, v[32:35], s[24:25] offset:384
	s_nop 1
	s_barrier
	s_branch .LBB0_664
